# in-proj and out-proj also walk their row panels in reverse (Infinity-Cache reuse of the activations written last / residual read next)
# baseline (speedup 1.0000x reference)
; #define G5_LOAD(k0)                                                                 \
;   {                                                                                 \
;     _Pragma("unroll") for (int i_ = 0; i_ < 4; ++i_) ra[i_] = ldg16(Ap + (size_t)(i_ * 64) * lda + (k0)); \
;     _Pragma("unroll") for (int i_ = 0; i_ < 4; ++i_) rb[i_] = ldg16(Bp + (size_t)(i_ * 64) * ldb + (k0)); \
;   }
; #define G5_STORE(s)                                                                 \
;   {                                                                                 \
;     _Pragma("unroll") for (int i_ = 0; i_ < 4; ++i_) *(u32x4*)(Sw + (s) * STG + i_ * 64 * GS) = ra[i_]; \
;     _Pragma("unroll") for (int i_ = 0; i_ < 4; ++i_) *(u32x4*)(Sw + (s) * STG + 256 * GS + i_ * 64 * GS) = rb[i_]; \
;   }
; template <typename Epi>
; DI void gemm_tile512(const u16* __restrict__ A, int lda, const u16* __restrict__ Bt, int ldb, int K, char* lds_all, Epi epi) {
;     ...
;   const int nk = K >> 6;
;   __syncthreads();
;   G5_LOAD(0);
;   G5_STORE(0);
;   G5_LOAD(64);
;   __syncthreads();
; DI void gemm_phase(const Params& p, int layer, int mode, int nrows, char* lds_all) {
;     ...
;   const int jb = swz ? (blockIdx.x >> 3) : blockIdx.x, nj = swz ? (gridDim.x >> 3) : gridDim.x;
;   const int per = 2 * ntn, nsr = ntm >> 1;
;   for (int i = jb;; i += nj) {
;     const int srl = i / per, rem = i - srl * per;
;     const int sr = xcd + nx * srl;
;     if (sr >= nsr) break;
;     const int tn = rem >> 1, tm = sr * 2 + (rem & 1);
;     const int m0 = tm * 256, n0 = tn * 256;
;     gemm_tile512(A + (size_t)m0 * lda, lda, Bt + (size_t)n0 * ldb, ldb, K, lds_all, [&](int half) {
.LBB0_198:
	s_sub_i32 s5, 16, s4
	s_lshl_b32 s5, s5, 3
	s_add_i32 s5, s5, s19
	s_mul_i32 s6, s4, 0xffffffea
	s_lshl_b32 s11, s5, 9
	s_lshl_b32 s5, s16, 8
	s_add_i32 s6, s6, s16
	s_and_b32 s5, s5, 0x100
	s_or_b32 s17, s5, s11
	s_lshl_b32 s5, s6, 7
	s_and_b32 s18, s5, 0xffffff00
	s_mul_i32 s6, s17, 0x900
	v_readlane_b32 s7, v250, 46
	s_mul_hi_i32 s5, s17, 0x900
	s_add_u32 s6, s7, s6
	v_readlane_b32 s7, v250, 47
	s_addc_u32 s7, s7, s5
	s_mul_i32 s8, s18, 0x900
	s_mul_hi_i32 s5, s18, 0x900
	s_add_u32 s8, s2, s8
	s_addc_u32 s9, s3, s5
	s_mov_b64 s[98:99], s[6:7]
	s_mov_b64 s[100:101], s[8:9]
	v_lshrrev_b32_e32 v239, 3, v165
	v_and_b32_e32 v0, 7, v165
	v_mul_u32_u24_e32 v206, 0x900, v239
	v_lshl_add_u32 v206, v0, 4, v206
	v_add_u32_e32 v207, 0x24000, v206
	v_add_u32_e32 v208, 0x48000, v206
	v_add_u32_e32 v238, 0x6c000, v206
	global_load_dwordx4 v[130:133], v206, s[98:99]
	global_load_dwordx4 v[134:137], v207, s[98:99]
	global_load_dwordx4 v[138:141], v208, s[98:99]
	global_load_dwordx4 v[142:145], v238, s[98:99]
	global_load_dwordx4 v[146:149], v206, s[100:101]
	global_load_dwordx4 v[150:153], v207, s[100:101]
	global_load_dwordx4 v[154:157], v208, s[100:101]
	global_load_dwordx4 v[158:161], v238, s[100:101]
	global_load_dwordx4 v[218:221], v206, s[98:99] offset:128
	global_load_dwordx4 v[222:225], v207, s[98:99] offset:128
	global_load_dwordx4 v[226:229], v208, s[98:99] offset:128
	global_load_dwordx4 v[230:233], v238, s[98:99] offset:128
	global_load_dwordx4 v[166:169], v206, s[100:101] offset:128
	global_load_dwordx4 v[170:173], v207, s[100:101] offset:128
	global_load_dwordx4 v[174:177], v208, s[100:101] offset:128
	global_load_dwordx4 v[190:193], v238, s[100:101] offset:128
	s_add_u32 s98, s98, 0x100
	s_addc_u32 s99, s99, 0
	s_add_u32 s100, s100, 0x100
	s_addc_u32 s101, s101, 0
	global_load_dwordx4 v[66:69], v206, s[98:99]
	global_load_dwordx4 v[70:73], v207, s[98:99]
	global_load_dwordx4 v[74:77], v208, s[98:99]
	global_load_dwordx4 v[78:81], v238, s[98:99]
	global_load_dwordx4 v[82:85], v206, s[100:101]
	global_load_dwordx4 v[86:89], v207, s[100:101]
	global_load_dwordx4 v[90:93], v208, s[100:101]
	global_load_dwordx4 v[94:97], v238, s[100:101]
	v_lshrrev_b32_e32 v239, 3, v165
	v_and_b32_e32 v0, 7, v165
	v_mul_u32_u24_e32 v180, 0x90, v239
	v_lshl_add_u32 v180, v0, 4, v180
	v_and_b32_e32 v239, 31, v165
	v_bfe_u32 v0, v165, 5, 1
	v_lshrrev_b32_e32 v179, 8, v165
	v_lshl_or_b32 v178, v179, 7, v239
	v_mul_u32_u24_e32 v178, 0x90, v178
	v_lshl_add_u32 v178, v0, 4, v178
	v_bfe_u32 v179, v165, 6, 2
	v_lshl_or_b32 v179, v179, 6, v239
	v_mul_u32_u24_e32 v179, 0x90, v179
	v_lshl_add_u32 v179, v0, 4, v179
	s_mov_b32 s12, 0x12000
	s_mov_b32 s13, 12
	s_barrier
	s_waitcnt vmcnt(23)
	ds_write_b128 v180, v[130:133]
	s_waitcnt vmcnt(22)
	ds_write_b128 v180, v[134:137] offset:9216
	s_waitcnt vmcnt(21)
	ds_write_b128 v180, v[138:141] offset:18432
	s_waitcnt vmcnt(20)
	ds_write_b128 v180, v[142:145] offset:27648
	s_waitcnt vmcnt(19)
	ds_write_b128 v180, v[146:149] offset:36864
	s_waitcnt vmcnt(18)
	ds_write_b128 v180, v[150:153] offset:46080
	s_waitcnt vmcnt(17)
	ds_write_b128 v180, v[154:157] offset:55296
	s_waitcnt vmcnt(16)
	ds_write_b128 v180, v[158:161] offset:64512
	v_add_u32_e32 v180, 0x12000, v180
	s_waitcnt vmcnt(15)
	ds_write_b128 v180, v[218:221]
	s_waitcnt vmcnt(14)
	ds_write_b128 v180, v[222:225] offset:9216
	s_waitcnt vmcnt(13)
	ds_write_b128 v180, v[226:229] offset:18432
	s_waitcnt vmcnt(12)
	ds_write_b128 v180, v[230:233] offset:27648
	s_waitcnt vmcnt(11)
	ds_write_b128 v180, v[166:169] offset:36864
	s_waitcnt vmcnt(10)
	ds_write_b128 v180, v[170:173] offset:46080
	s_waitcnt vmcnt(9)
	ds_write_b128 v180, v[174:177] offset:55296
	s_waitcnt vmcnt(8)
	ds_write_b128 v180, v[190:193] offset:64512
	s_waitcnt vmcnt(0)
	v_mov_b64_e32 v[130:131], v[66:67]
	v_mov_b64_e32 v[132:133], v[68:69]
	v_mov_b64_e32 v[134:135], v[70:71]
	v_mov_b64_e32 v[136:137], v[72:73]
	v_mov_b64_e32 v[138:139], v[74:75]
	v_mov_b64_e32 v[140:141], v[76:77]
	v_mov_b64_e32 v[142:143], v[78:79]
	v_mov_b64_e32 v[144:145], v[80:81]
	v_mov_b64_e32 v[146:147], v[82:83]
	v_mov_b64_e32 v[148:149], v[84:85]
	v_mov_b64_e32 v[150:151], v[86:87]
	v_mov_b64_e32 v[152:153], v[88:89]
	v_mov_b64_e32 v[154:155], v[90:91]
	v_mov_b64_e32 v[156:157], v[92:93]
	v_mov_b64_e32 v[158:159], v[94:95]
	v_mov_b64_e32 v[160:161], v[96:97]
	s_waitcnt lgkmcnt(0)
	s_branch .Lg3_k_m0

; DI void gemm_phase(const Params& p, int layer, int mode, int nrows, char* lds_all) {
;     ...
;   for (int i = jb;; i += nj) {
;     const int srl = i / per, rem = i - srl * per;
;     const int sr = xcd + nx * srl;
;     if (sr >= nsr) break;
;     const int tn = rem >> 1, tm = sr * 2 + (rem & 1);
;     const int m0 = tm * 256, n0 = tn * 256;
;     gemm_tile512(A + (size_t)m0 * lda, lda, Bt + (size_t)n0 * ldb, ldb, K, lds_all, [&](int half) {
;     ...
;             *(uint4*)((u16*)(p.ws + O_Z) + (size_t)row * ZW + col) = o;
.Lepi0_nograw:
	s_mul_i32 s10, s17, 0x1600
	s_lshl_b32 s20, s18, 1
	s_add_u32 s10, s10, s20
	v_lshrrev_b32_e32 v237, 5, v165
	v_and_b32_e32 v194, 31, v165
	v_mul_u32_u24_e32 v234, 0x1600, v237
	v_lshl_add_u32 v234, v194, 4, v234
	v_add_u32_e32 v234, s10, v234
	v_readlane_b32 s4, v251, 9
	s_add_i32 s16, s16, s4
	s_mul_hi_i32 s4, s16, 0x2e8ba2e9
	s_lshr_b32 s5, s4, 31
	s_ashr_i32 s4, s4, 2
	s_add_i32 s4, s4, s5
	v_readlane_b32 s5, v252, 2
	v_readlane_b32 s6, v252, 6
	s_lshl_b32 s5, s4, s5
	s_add_i32 s15, s15, s6
	v_readlane_b32 s6, v252, 9
	s_add_i32 s5, s5, s19
	s_add_i32 s14, s14, s6
	s_cmpk_lt_i32 s5, 0x88
	s_cselect_b32 s10, 1, 0
	s_cmp_eq_u32 s10, 0
	s_cbranch_scc1 .Lg3_nonext_m0
	s_sub_i32 s5, 16, s4
	s_lshl_b32 s5, s5, 3
	s_add_i32 s5, s5, s19
	s_mul_i32 s6, s4, 0xffffffea
	s_lshl_b32 s11, s5, 9
	s_lshl_b32 s5, s16, 8
	s_add_i32 s6, s6, s16
	s_and_b32 s5, s5, 0x100
	s_or_b32 s17, s5, s11
	s_lshl_b32 s5, s6, 7
	s_and_b32 s18, s5, 0xffffff00
	s_mul_i32 s6, s17, 0x900
	v_readlane_b32 s7, v250, 46
	s_mul_hi_i32 s5, s17, 0x900
	s_add_u32 s6, s7, s6
	v_readlane_b32 s7, v250, 47
	s_addc_u32 s7, s7, s5
	s_mul_i32 s8, s18, 0x900
	s_mul_hi_i32 s5, s18, 0x900
	s_add_u32 s8, s2, s8
	s_addc_u32 s9, s3, s5
	s_mov_b64 s[98:99], s[6:7]
	s_mov_b64 s[100:101], s[8:9]
	v_lshrrev_b32_e32 v239, 3, v165
	v_and_b32_e32 v0, 7, v165
	v_mul_u32_u24_e32 v206, 0x900, v239
	v_lshl_add_u32 v206, v0, 4, v206
	v_add_u32_e32 v207, 0x24000, v206
	v_add_u32_e32 v208, 0x48000, v206
	v_add_u32_e32 v238, 0x6c000, v206
	global_load_dwordx4 v[130:133], v206, s[98:99]
	global_load_dwordx4 v[134:137], v207, s[98:99]
	global_load_dwordx4 v[138:141], v208, s[98:99]
	global_load_dwordx4 v[142:145], v238, s[98:99]
	global_load_dwordx4 v[146:149], v206, s[100:101]
	global_load_dwordx4 v[150:153], v207, s[100:101]
	global_load_dwordx4 v[154:157], v208, s[100:101]
	global_load_dwordx4 v[158:161], v238, s[100:101]
	global_load_dwordx4 v[218:221], v206, s[98:99] offset:128
	global_load_dwordx4 v[222:225], v207, s[98:99] offset:128
	global_load_dwordx4 v[226:229], v208, s[98:99] offset:128
	global_load_dwordx4 v[230:233], v238, s[98:99] offset:128
	global_load_dwordx4 v[166:169], v206, s[100:101] offset:128
	global_load_dwordx4 v[170:173], v207, s[100:101] offset:128
	global_load_dwordx4 v[174:177], v208, s[100:101] offset:128
	global_load_dwordx4 v[190:193], v238, s[100:101] offset:128
	s_add_u32 s98, s98, 0x100
	s_addc_u32 s99, s99, 0
	s_add_u32 s100, s100, 0x100
	s_addc_u32 s101, s101, 0

; #define G5_LOAD(k0)                                                                 \
;   {                                                                                 \
;     _Pragma("unroll") for (int i_ = 0; i_ < 4; ++i_) ra[i_] = ldg16(Ap + (size_t)(i_ * 64) * lda + (k0)); \
;     _Pragma("unroll") for (int i_ = 0; i_ < 4; ++i_) rb[i_] = ldg16(Bp + (size_t)(i_ * 64) * ldb + (k0)); \
;   }
; #define G5_STORE(s)                                                                 \
;   {                                                                                 \
;     _Pragma("unroll") for (int i_ = 0; i_ < 4; ++i_) *(u32x4*)(Sw + (s) * STG + i_ * 64 * GS) = ra[i_]; \
;     _Pragma("unroll") for (int i_ = 0; i_ < 4; ++i_) *(u32x4*)(Sw + (s) * STG + 256 * GS + i_ * 64 * GS) = rb[i_]; \
;   }
; template <typename Epi>
; DI void gemm_tile512(const u16* __restrict__ A, int lda, const u16* __restrict__ Bt, int ldb, int K, char* lds_all, Epi epi) {
;     ...
;   const int nk = K >> 6;
;   __syncthreads();
;   G5_LOAD(0);
;   G5_STORE(0);
;   G5_LOAD(64);
;   __syncthreads();
;   for (int kt = 0; kt + 2 < nk; ++kt) {
;     const int cur = kt & 1;
;     G5_COMPUTE(cur);
;     G5_STORE(cur ^ 1);
;     G5_LOAD((kt + 2) << 6);
;     __syncthreads();
;   }
; DI void gemm_phase(const Params& p, int layer, int mode, int nrows, char* lds_all) {
;     ...
;   for (int i = jb;; i += nj) {
;     const int srl = i / per, rem = i - srl * per;
;     const int sr = xcd + nx * srl;
;     if (sr >= nsr) break;
;     const int tn = rem >> 1, tm = sr * 2 + (rem & 1);
;     const int m0 = tm * 256, n0 = tn * 256;
;     gemm_tile512(A + (size_t)m0 * lda, lda, Bt + (size_t)n0 * ldb, ldb, K, lds_all, [&](int half) {
.LBB0_789:
	s_sub_i32 s17, s36, s19
	s_add_i32 s17, s17, 7
	s_lshr_b32 s17, s17, 3
	s_sub_i32 s17, s17, 1
	s_sub_i32 s17, s17, s12
	s_lshl_b32 s17, s17, 3
	s_add_i32 s13, s17, s19
	s_lshl_b32 s17, s13, 9
	s_lshl_b32 s13, s26, 8
	s_and_b32 s13, s13, 0x100
	s_lshl_b32 s29, s12, 10
	s_lshl_b32 s12, s26, 7
	s_or_b32 s27, s13, s17
	s_sub_i32 s12, s12, s29
	s_and_b32 s28, s12, 0xffffff00
	s_mul_i32 s12, s27, 0x900
	v_readlane_b32 s14, v250, 46
	s_mul_hi_i32 s13, s27, 0x900
	s_add_u32 s12, s14, s12
	v_readlane_b32 s14, v250, 47
	s_addc_u32 s13, s14, s13
	s_mul_i32 s14, s28, 0x900
	s_mul_hi_i32 s15, s28, 0x900
	s_add_u32 s14, s38, s14
	s_addc_u32 s15, s39, s15
	s_mov_b64 s[98:99], s[12:13]
	s_mov_b64 s[100:101], s[14:15]
	v_lshrrev_b32_e32 v239, 3, v165
	v_and_b32_e32 v0, 7, v165
	v_mul_u32_u24_e32 v206, 0x900, v239
	v_lshl_add_u32 v206, v0, 4, v206
	v_add_u32_e32 v207, 0x24000, v206
	v_add_u32_e32 v208, 0x48000, v206
	v_add_u32_e32 v238, 0x6c000, v206
	v_mul_u32_u24_e32 v180, 0x90, v239
	v_lshl_add_u32 v180, v0, 4, v180
	global_load_dwordx4 v[2:5], v206, s[98:99]
	global_load_dwordx4 v[6:9], v207, s[98:99]
	global_load_dwordx4 v[10:13], v208, s[98:99]
	global_load_dwordx4 v[14:17], v238, s[98:99]
	global_load_dwordx4 v[18:21], v206, s[100:101]
	global_load_dwordx4 v[22:25], v207, s[100:101]
	global_load_dwordx4 v[26:29], v208, s[100:101]
	global_load_dwordx4 v[30:33], v238, s[100:101]
	global_load_dwordx4 v[130:133], v206, s[98:99] offset:128
	global_load_dwordx4 v[134:137], v207, s[98:99] offset:128
	global_load_dwordx4 v[138:141], v208, s[98:99] offset:128
	global_load_dwordx4 v[142:145], v238, s[98:99] offset:128
	global_load_dwordx4 v[146:149], v206, s[100:101] offset:128
	global_load_dwordx4 v[150:153], v207, s[100:101] offset:128
	global_load_dwordx4 v[154:157], v208, s[100:101] offset:128
	global_load_dwordx4 v[158:161], v238, s[100:101] offset:128
	s_add_u32 s98, s98, 0x100
	s_addc_u32 s99, s99, 0
	s_add_u32 s100, s100, 0x100
	s_addc_u32 s101, s101, 0
	v_and_b32_e32 v239, 31, v165
	v_bfe_u32 v0, v165, 5, 1
	v_lshrrev_b32_e32 v179, 8, v165
	v_lshl_or_b32 v178, v179, 7, v239
	v_mul_u32_u24_e32 v178, 0x90, v178
	v_lshl_add_u32 v178, v0, 4, v178
	v_bfe_u32 v179, v165, 6, 2
	v_lshl_or_b32 v179, v179, 6, v239
	v_mul_u32_u24_e32 v179, 0x90, v179
	v_lshl_add_u32 v179, v0, 4, v179
	s_mov_b32 s20, 0x12000
	s_mov_b32 s21, 13
	s_barrier
	s_waitcnt vmcnt(15)
	ds_write_b128 v180, v[2:5]
	s_waitcnt vmcnt(14)
	ds_write_b128 v180, v[6:9] offset:9216
	s_waitcnt vmcnt(13)
	ds_write_b128 v180, v[10:13] offset:18432
	s_waitcnt vmcnt(12)
	ds_write_b128 v180, v[14:17] offset:27648
	s_waitcnt vmcnt(11)
	ds_write_b128 v180, v[18:21] offset:36864
	s_waitcnt vmcnt(10)
	ds_write_b128 v180, v[22:25] offset:46080
	s_waitcnt vmcnt(9)
	ds_write_b128 v180, v[26:29] offset:55296
	s_waitcnt vmcnt(8)
	ds_write_b128 v180, v[30:33] offset:64512
	v_add_u32_e32 v180, 0x12000, v180
	s_waitcnt lgkmcnt(0)
	s_barrier
	ds_read_b128 v[194:197], v179 offset:36864
	ds_read_b128 v[166:169], v178
	ds_read_b128 v[198:201], v179 offset:41472
	ds_read_b128 v[170:173], v178 offset:4608
	ds_read_b128 v[174:177], v178 offset:9216
	ds_read_b128 v[190:193], v178 offset:13824
	s_waitcnt lgkmcnt(4)
	v_mfma_f32_32x32x16_bf16 v[114:129], v[166:169], v[194:197], 0
	ds_read_b128 v[234:237], v179 offset:36896
	s_waitcnt lgkmcnt(4)
	v_mfma_f32_32x32x16_bf16 v[98:113], v[166:169], v[198:201], 0
	ds_read_b128 v[218:221], v178 offset:32
	s_waitcnt vmcnt(7)
	ds_write_b128 v180, v[130:133]
	global_load_dwordx4 v[130:133], v206, s[98:99]
	s_waitcnt lgkmcnt(5)
	v_mfma_f32_32x32x16_bf16 v[82:97], v[170:173], v[194:197], 0
	ds_read_b128 v[202:205], v179 offset:41504
	v_mfma_f32_32x32x16_bf16 v[66:81], v[170:173], v[198:201], 0
	ds_read_b128 v[222:225], v178 offset:4640
	s_waitcnt vmcnt(7)
	ds_write_b128 v180, v[134:137] offset:9216
	global_load_dwordx4 v[134:137], v207, s[98:99]
	s_waitcnt lgkmcnt(7)
	v_mfma_f32_32x32x16_bf16 v[50:65], v[174:177], v[194:197], 0
	ds_read_b128 v[226:229], v178 offset:9248
	v_mfma_f32_32x32x16_bf16 v[34:49], v[174:177], v[198:201], 0
	ds_read_b128 v[230:233], v178 offset:13856
	s_waitcnt vmcnt(7)
	ds_write_b128 v180, v[138:141] offset:18432
	global_load_dwordx4 v[138:141], v208, s[98:99]
	s_waitcnt lgkmcnt(9)
	v_mfma_f32_32x32x16_bf16 v[18:33], v[190:193], v[194:197], 0
	v_mfma_f32_32x32x16_bf16 v[2:17], v[190:193], v[198:201], 0
	s_waitcnt vmcnt(7)
	ds_write_b128 v180, v[142:145] offset:27648
	global_load_dwordx4 v[142:145], v238, s[98:99]
	s_waitcnt lgkmcnt(8)
	v_mfma_f32_32x32x16_bf16 v[114:129], v[218:221], v[234:237], v[114:129]
	ds_read_b128 v[194:197], v179 offset:36928
	s_waitcnt lgkmcnt(7)
	v_mfma_f32_32x32x16_bf16 v[98:113], v[218:221], v[202:205], v[98:113]
	ds_read_b128 v[166:169], v178 offset:64
	s_waitcnt vmcnt(7)
	ds_write_b128 v180, v[146:149] offset:36864
	global_load_dwordx4 v[146:149], v206, s[100:101]
	s_waitcnt lgkmcnt(8)
	v_mfma_f32_32x32x16_bf16 v[82:97], v[222:225], v[234:237], v[82:97]
	ds_read_b128 v[198:201], v179 offset:41536
	v_mfma_f32_32x32x16_bf16 v[66:81], v[222:225], v[202:205], v[66:81]
	ds_read_b128 v[170:173], v178 offset:4672
	s_waitcnt vmcnt(7)
	ds_write_b128 v180, v[150:153] offset:46080
	global_load_dwordx4 v[150:153], v207, s[100:101]
	s_waitcnt lgkmcnt(9)
	v_mfma_f32_32x32x16_bf16 v[50:65], v[226:229], v[234:237], v[50:65]
	ds_read_b128 v[174:177], v178 offset:9280
	v_mfma_f32_32x32x16_bf16 v[34:49], v[226:229], v[202:205], v[34:49]
	ds_read_b128 v[190:193], v178 offset:13888
	s_waitcnt vmcnt(7)
	ds_write_b128 v180, v[154:157] offset:55296
	global_load_dwordx4 v[154:157], v208, s[100:101]
	s_waitcnt lgkmcnt(11)
	v_mfma_f32_32x32x16_bf16 v[18:33], v[230:233], v[234:237], v[18:33]
	v_mfma_f32_32x32x16_bf16 v[2:17], v[230:233], v[202:205], v[2:17]
	s_waitcnt vmcnt(7)
	ds_write_b128 v180, v[158:161] offset:64512
	global_load_dwordx4 v[158:161], v238, s[100:101]
	v_subrev_u32_e32 v180, s20, v180
	s_waitcnt lgkmcnt(8)
	v_mfma_f32_32x32x16_bf16 v[114:129], v[166:169], v[194:197], v[114:129]
	ds_read_b128 v[234:237], v179 offset:36960
	s_waitcnt lgkmcnt(7)
	v_mfma_f32_32x32x16_bf16 v[98:113], v[166:169], v[198:201], v[98:113]
	ds_read_b128 v[218:221], v178 offset:96
	s_waitcnt lgkmcnt(7)
	v_mfma_f32_32x32x16_bf16 v[82:97], v[170:173], v[194:197], v[82:97]
	ds_read_b128 v[202:205], v179 offset:41568
	v_mfma_f32_32x32x16_bf16 v[66:81], v[170:173], v[198:201], v[66:81]
	ds_read_b128 v[222:225], v178 offset:4704
	s_waitcnt lgkmcnt(7)
	v_mfma_f32_32x32x16_bf16 v[50:65], v[174:177], v[194:197], v[50:65]
	ds_read_b128 v[226:229], v178 offset:9312
	v_mfma_f32_32x32x16_bf16 v[34:49], v[174:177], v[198:201], v[34:49]
	ds_read_b128 v[230:233], v178 offset:13920
	v_add_u32_e32 v178, s20, v178
	v_add_u32_e32 v179, s20, v179
	s_waitcnt lgkmcnt(8)
	v_mfma_f32_32x32x16_bf16 v[18:33], v[190:193], v[194:197], v[18:33]
	v_mfma_f32_32x32x16_bf16 v[2:17], v[190:193], v[198:201], v[2:17]
	s_sub_u32 s20, 0, s20
	s_add_u32 s98, s98, 0x80
	s_addc_u32 s99, s99, 0
	s_add_u32 s100, s100, 0x80
	s_addc_u32 s101, s101, 0
	s_waitcnt lgkmcnt(0)
